# diff attention: K/V staged by LDS-DMA into XOR-swizzled unpadded tiles (no VGPR staging / ds_write); GQA as previous version
# speedup vs baseline: 1.0058x; 1.0058x over previous
; #define LAS __attribute__((address_space(3)))
; template <int KIND> ...
;     ...
;             if (t + 1 < nt) ATT_LOAD(t + 1);
;             bool active = true;
;             if (KIND == 0 && t < n1) { const int kr = kr_lo + t; active = (kr >= rs_w) && (kr < rs_w + 8); }
;             if (__builtin_amdgcn_readfirstlane((int)active)) {
;                 const int buf = t & 1;
;                 bf16x8 kf[8];
; #pragma unroll
;                 for (int t4 = 0; t4 < 4; ++t4) { kf[2 * t4] = *(const LAS bf16x8*)(lds + buf * KBUF + koff + 32 * t4); kf[2 * t4 + 1] = *(const LAS bf16x8*)(lds + buf * KBUF + koff + 32 * KSTR + 32 * t4); }
;                 __builtin_amdgcn_sched_barrier(0);
;                 f32x16 s0, s1;
; #pragma unroll
;                 for (int t4 = 0; t4 < 4; ++t4) {
;                     s0 = __builtin_amdgcn_mfma_f32_32x32x16_bf16(kf[2 * t4], qf[t4], t4 == 0 ? mneg : s0, 0, 0, 0);
;                     s1 = __builtin_amdgcn_mfma_f32_32x32x16_bf16(kf[2 * t4 + 1], qf[t4], t4 == 0 ? mneg : s1, 0, 0, 0);
;                 }
;                 float ab0[16], ab1[16];
;                 const bool na_lat = (KIND == 0) && (t < n1);
;                 if (na_lat) {
;                     const int bo = boff0 + (kr_lo + t - qr + 7) * 124;
; #pragma unroll
;                     for (int j = 0; j < 16; ++j) {
;                         const int C0 = 8 * (j >> 2) + (j & 3), C1 = 32 + C0;
;                         const float b0 = *(const LAS float*)(lds + bo + 4 * C0), b1 = *(const LAS float*)(lds + bo + 4 * C1);
;                         ab0[j] = ((unsigned)(wb + C0) < 16u) ? b0 : -1e30f;
;                         ab1[j] = ((unsigned)(wb + C1) < 16u) ? b1 : -1e30f;
;                     }
; #pragma unroll
;                     for (int i = 0; i < 8; ++i) { __builtin_amdgcn_sched_group_barrier(0x008, 1, 0); __builtin_amdgcn_sched_group_barrier(0x100, 4, 0); __builtin_amdgcn_sched_group_barrier(0x002, 12, 0); }
;                 }
;                 __builtin_amdgcn_sched_barrier(0);
;                 s16x4 vfa[2][NDT][2], vfb[2][NDT][2];
; #pragma unroll
;                 for (int s = 0; s < 2; ++s)
; #pragma unroll
;                     for (int dt = 0; dt < NDT; ++dt) {
;                         vfa[s][dt][0] = __builtin_amdgcn_ds_read_tr16_b64_v4i16((LAS s16x4*)(lds + buf * VBUF + voff + (16 * s) * VSTR + 64 * dt));
.LBB0_189:
	s_add_i32 s17, s16, 5
	s_cmp_lt_u32 s17, s26
	s_cselect_b64 s[4:5], -1, 0
	s_cmp_ge_u32 s17, s26
	s_cbranch_scc1 .LBB0_191
	s_cmp_lt_u32 s17, s3
	s_cselect_b32 s27, 0, s3
	s_cselect_b32 s28, s2, s15
	s_lshl_b32 s27, s27, 6
	s_sub_i32 s27, s28, s27
	v_add_u32_e32 v96, s27, v248
	s_movk_i32 s30, 0x1800
	s_and_b32 s29, s17, 1
	s_lshl_b32 s29, s29, 14
	s_add_i32 s29, s29, s18
	v_mad_i64_i32 v[96:97], vcc, v96, s30, v[210:211]
	s_mov_b32 m0, s29
	v_add_u32_e32 v98, s27, v249
	global_load_lds_dwordx4 v[96:97], off
	s_add_i32 m0, s29, 0x1c00
	v_mad_i64_i32 v[98:99], vcc, v98, s30, v[212:213]
	global_load_lds_dwordx4 v[96:97], off offset:1024
	s_add_i32 m0, s29, 0x8000
	v_add_u32_e32 v96, s27, v250
	global_load_lds_dwordx4 v[98:99], off
	v_mad_i64_i32 v[96:97], vcc, v96, s30, v[214:215]
	s_add_i32 m0, s29, 0xa000
	s_nop 0
	global_load_lds_dwordx4 v[96:97], off
.LBB0_191:
	s_add_i32 s27, s16, 4
	s_and_b32 s27, s27, 1
	s_lshl_b32 s28, s27, 14
	v_add_u32_e32 v100, s28, v235
	v_xor_b32_e32 v144, 32, v100
	v_xor_b32_e32 v145, 64, v100
	v_xor_b32_e32 v146, 0x60, v100
	ds_read_b128 v[96:99], v100
	ds_read_b128 v[160:163], v144
	ds_read_b128 v[164:167], v100 offset:4096
	ds_read_b128 v[168:171], v144 offset:4096
	ds_read_b128 v[172:175], v145
	ds_read_b128 v[218:221], v146
	ds_read_b128 v[176:179], v145 offset:4096
	ds_read_b128 v[230:233], v146 offset:4096
	s_waitcnt lgkmcnt(7)
	v_mfma_f32_32x32x16_bf16 v[112:127], v[96:99], v[128:131], v[64:79]
	s_lshl_b32 s27, s27, 14
	v_add_u32_e32 v251, s27, v236
	v_xor_b32_e32 v147, 64, v251
	v_xor_b32_e32 v148, 0x80, v251
	v_xor_b32_e32 v149, 0xc0, v251
	s_waitcnt lgkmcnt(5)
	v_mfma_f32_32x32x16_bf16 v[96:111], v[164:167], v[128:131], v[64:79]
	v_mfma_f32_32x32x16_bf16 v[112:127], v[160:163], v[132:135], v[112:127]
	s_waitcnt lgkmcnt(4)
	v_mfma_f32_32x32x16_bf16 v[96:111], v[168:171], v[132:135], v[96:111]
	s_waitcnt lgkmcnt(3)
	v_mfma_f32_32x32x16_bf16 v[112:127], v[172:175], v[136:139], v[112:127]
	s_waitcnt lgkmcnt(1)
	v_mfma_f32_32x32x16_bf16 v[96:111], v[176:179], v[136:139], v[96:111]
	ds_read_b64_tr_b16 v[188:189], v251 offset:32768
	ds_read_b64_tr_b16 v[184:185], v147 offset:32768
	ds_read_b64_tr_b16 v[180:181], v148 offset:32768
	ds_read_b64_tr_b16 v[176:177], v149 offset:32768
	ds_read_b64_tr_b16 v[190:191], v251 offset:34816
	ds_read_b64_tr_b16 v[186:187], v147 offset:34816
	ds_read_b64_tr_b16 v[182:183], v148 offset:34816
	ds_read_b64_tr_b16 v[178:179], v149 offset:34816
	ds_read_b64_tr_b16 v[172:173], v251 offset:36864
	ds_read_b64_tr_b16 v[168:169], v147 offset:36864
	ds_read_b64_tr_b16 v[164:165], v148 offset:36864
	ds_read_b64_tr_b16 v[160:161], v149 offset:36864
	ds_read_b64_tr_b16 v[174:175], v251 offset:38912
	ds_read_b64_tr_b16 v[170:171], v147 offset:38912
	ds_read_b64_tr_b16 v[166:167], v148 offset:38912
	ds_read_b64_tr_b16 v[162:163], v149 offset:38912
	v_mfma_f32_32x32x16_bf16 v[112:127], v[218:221], v[140:143], v[112:127]
	s_waitcnt lgkmcnt(14)
	v_mfma_f32_32x32x16_bf16 v[96:111], v[230:233], v[140:143], v[96:111]
	s_nop 9
	v_max_f32_e32 v218, v127, v127
	s_nop 0
	v_max_f32_e32 v219, v111, v111
	v_max_f32_e32 v218, v219, v218
	v_max3_f32 v219, v218, v112, v96
	v_max3_f32 v218, v218, v113, v97
	s_nop 0
	v_max3_f32 v219, v219, v114, v98
	v_max3_f32 v218, v218, v115, v99
	s_nop 0
	v_max3_f32 v219, v219, v116, v100
	v_max3_f32 v218, v218, v117, v101
	s_nop 0
	v_max3_f32 v219, v219, v118, v102
	v_max3_f32 v218, v218, v119, v103
	s_nop 0
	v_max3_f32 v219, v219, v120, v104
	v_max3_f32 v218, v218, v121, v105
	s_nop 0
	v_max3_f32 v219, v219, v122, v106
	v_max3_f32 v218, v218, v123, v107
	s_nop 0
	v_max3_f32 v219, v219, v124, v108
	v_max3_f32 v218, v218, v125, v109
	s_nop 0
	v_max3_f32 v219, v219, v126, v110
	v_max3_f32 v218, v218, v127, v111
	s_nop 0
	v_max_f32_e32 v218, v218, v218
	v_max_f32_e32 v219, v219, v219
	v_max_f32_e32 v252, v219, v218
	v_cmp_lt_f32_e32 vcc, s31, v252
	s_cbranch_vccz .LBB0_193
; template <int KIND> ...
;     ...
;                 if (first || __builtin_amdgcn_ballot_w64(mx > 8.0f) != 0ull) {
;                     mx = fmaxf(mx, __shfl_xor(mx, 32));
;                     const float d = first ? mx : fmaxf(mx, 0.f);
;                     const float alpha = first ? 1.0f : __builtin_amdgcn_exp2f(-d);
;                     m_ref += d;
; #pragma unroll
;                     for (int j = 0; j < 16; ++j) { mneg[j] -= d; s0[j] -= d; s1[j] -= d; lacc[j] *= alpha; }
; #pragma unroll
;                     for (int dt = 0; dt < NDT; ++dt)
; #pragma unroll
;                         for (int j = 0; j < 16; ++j) o[dt][j] *= alpha;
;                     first = 0;
;                 }
	ds_bpermute_b32 v218, v197, v252
	s_waitcnt lgkmcnt(0)
	v_max3_f32 v218, v252, v218, 0
	v_exp_f32_e64 v220, -v218
	v_pk_add_f32 v[112:113], v[112:113], v[218:219] op_sel_hi:[1,0] neg_lo:[0,1] neg_hi:[0,1]
	v_pk_add_f32 v[96:97], v[96:97], v[218:219] op_sel_hi:[1,0] neg_lo:[0,1] neg_hi:[0,1]
	v_pk_add_f32 v[114:115], v[114:115], v[218:219] op_sel_hi:[1,0] neg_lo:[0,1] neg_hi:[0,1]
	v_pk_add_f32 v[98:99], v[98:99], v[218:219] op_sel_hi:[1,0] neg_lo:[0,1] neg_hi:[0,1]
	v_pk_add_f32 v[116:117], v[116:117], v[218:219] op_sel_hi:[1,0] neg_lo:[0,1] neg_hi:[0,1]
	v_pk_add_f32 v[100:101], v[100:101], v[218:219] op_sel_hi:[1,0] neg_lo:[0,1] neg_hi:[0,1]
	v_pk_add_f32 v[118:119], v[118:119], v[218:219] op_sel_hi:[1,0] neg_lo:[0,1] neg_hi:[0,1]
	v_pk_add_f32 v[102:103], v[102:103], v[218:219] op_sel_hi:[1,0] neg_lo:[0,1] neg_hi:[0,1]
	v_pk_add_f32 v[120:121], v[120:121], v[218:219] op_sel_hi:[1,0] neg_lo:[0,1] neg_hi:[0,1]
	v_pk_add_f32 v[104:105], v[104:105], v[218:219] op_sel_hi:[1,0] neg_lo:[0,1] neg_hi:[0,1]
	v_pk_add_f32 v[122:123], v[122:123], v[218:219] op_sel_hi:[1,0] neg_lo:[0,1] neg_hi:[0,1]
	v_pk_add_f32 v[106:107], v[106:107], v[218:219] op_sel_hi:[1,0] neg_lo:[0,1] neg_hi:[0,1]
	v_pk_add_f32 v[124:125], v[124:125], v[218:219] op_sel_hi:[1,0] neg_lo:[0,1] neg_hi:[0,1]
	v_pk_add_f32 v[108:109], v[108:109], v[218:219] op_sel_hi:[1,0] neg_lo:[0,1] neg_hi:[0,1]
	v_pk_add_f32 v[126:127], v[126:127], v[218:219] op_sel_hi:[1,0] neg_lo:[0,1] neg_hi:[0,1]
	v_pk_add_f32 v[110:111], v[110:111], v[218:219] op_sel_hi:[1,0] neg_lo:[0,1] neg_hi:[0,1]
	v_pk_mul_f32 v[94:95], v[94:95], v[220:221] op_sel_hi:[1,0]
	v_pk_mul_f32 v[92:93], v[92:93], v[220:221] op_sel_hi:[1,0]
	v_pk_mul_f32 v[90:91], v[90:91], v[220:221] op_sel_hi:[1,0]
	v_pk_mul_f32 v[88:89], v[88:89], v[220:221] op_sel_hi:[1,0]
	v_pk_mul_f32 v[86:87], v[86:87], v[220:221] op_sel_hi:[1,0]
	v_pk_mul_f32 v[84:85], v[84:85], v[220:221] op_sel_hi:[1,0]
	v_pk_mul_f32 v[82:83], v[82:83], v[220:221] op_sel_hi:[1,0]
	v_pk_mul_f32 v[80:81], v[80:81], v[220:221] op_sel_hi:[1,0]
	v_pk_mul_f32 v[62:63], v[62:63], v[220:221] op_sel_hi:[1,0]
	v_pk_mul_f32 v[60:61], v[60:61], v[220:221] op_sel_hi:[1,0]
	v_pk_mul_f32 v[58:59], v[58:59], v[220:221] op_sel_hi:[1,0]
	v_pk_mul_f32 v[56:57], v[56:57], v[220:221] op_sel_hi:[1,0]
	v_pk_mul_f32 v[54:55], v[54:55], v[220:221] op_sel_hi:[1,0]
	v_pk_mul_f32 v[52:53], v[52:53], v[220:221] op_sel_hi:[1,0]
	v_pk_mul_f32 v[50:51], v[50:51], v[220:221] op_sel_hi:[1,0]
	v_pk_mul_f32 v[48:49], v[48:49], v[220:221] op_sel_hi:[1,0]
	v_pk_mul_f32 v[46:47], v[46:47], v[220:221] op_sel_hi:[1,0]
	v_pk_mul_f32 v[44:45], v[44:45], v[220:221] op_sel_hi:[1,0]
	v_pk_mul_f32 v[42:43], v[42:43], v[220:221] op_sel_hi:[1,0]
	v_pk_mul_f32 v[40:41], v[40:41], v[220:221] op_sel_hi:[1,0]
	v_pk_mul_f32 v[38:39], v[38:39], v[220:221] op_sel_hi:[1,0]
	v_pk_mul_f32 v[36:37], v[36:37], v[220:221] op_sel_hi:[1,0]
	v_pk_mul_f32 v[34:35], v[34:35], v[220:221] op_sel_hi:[1,0]
	v_pk_mul_f32 v[32:33], v[32:33], v[220:221] op_sel_hi:[1,0]
	v_pk_mul_f32 v[30:31], v[30:31], v[220:221] op_sel_hi:[1,0]
	v_pk_mul_f32 v[28:29], v[28:29], v[220:221] op_sel_hi:[1,0]
	v_pk_mul_f32 v[26:27], v[26:27], v[220:221] op_sel_hi:[1,0]
	v_pk_mul_f32 v[24:25], v[24:25], v[220:221] op_sel_hi:[1,0]
	v_pk_mul_f32 v[22:23], v[22:23], v[220:221] op_sel_hi:[1,0]
	v_pk_mul_f32 v[20:21], v[20:21], v[220:221] op_sel_hi:[1,0]
	v_pk_mul_f32 v[18:19], v[18:19], v[220:221] op_sel_hi:[1,0]
	v_pk_mul_f32 v[16:17], v[16:17], v[220:221] op_sel_hi:[1,0]
	v_pk_mul_f32 v[14:15], v[14:15], v[220:221] op_sel_hi:[1,0]
	v_pk_mul_f32 v[12:13], v[12:13], v[220:221] op_sel_hi:[1,0]
	v_pk_mul_f32 v[10:11], v[10:11], v[220:221] op_sel_hi:[1,0]
	v_pk_mul_f32 v[8:9], v[8:9], v[220:221] op_sel_hi:[1,0]
	v_pk_mul_f32 v[6:7], v[6:7], v[220:221] op_sel_hi:[1,0]
	v_pk_mul_f32 v[4:5], v[4:5], v[220:221] op_sel_hi:[1,0]
	v_pk_mul_f32 v[2:3], v[2:3], v[220:221] op_sel_hi:[1,0]
	v_pk_mul_f32 v[0:1], v[0:1], v[220:221] op_sel_hi:[1,0]
	v_sub_f32_e32 v79, v79, v218
	v_sub_f32_e32 v78, v78, v218
	v_sub_f32_e32 v77, v77, v218
	v_sub_f32_e32 v76, v76, v218
	v_sub_f32_e32 v75, v75, v218
	v_sub_f32_e32 v74, v74, v218
	v_sub_f32_e32 v73, v73, v218
	v_sub_f32_e32 v72, v72, v218
	v_sub_f32_e32 v71, v71, v218
	v_sub_f32_e32 v70, v70, v218
	v_sub_f32_e32 v69, v69, v218
	v_sub_f32_e32 v68, v68, v218
	v_sub_f32_e32 v67, v67, v218
	v_sub_f32_e32 v66, v66, v218
	v_sub_f32_e32 v65, v65, v218
	v_sub_f32_e32 v64, v64, v218
